# v26: GU epilogue row scales for blocks 2-7 read from LDS once after block 0 store (into freed acc regs), block 1 waits lgkmcnt(6)
# speedup vs baseline: 1.0089x; 1.0033x over previous
; #define PG8_LAS __attribute__((address_space(3)))
; __device__ __forceinline__ u32x4 pack8(const f32x4 a, const f32x4 b) { u32x4 w; w.x = cvt_pk_bf16(a[0], a[1]); w.y = cvt_pk_bf16(a[2], a[3]); w.z = cvt_pk_bf16(b[0], b[1]); w.w = cvt_pk_bf16(b[2], b[3]); return w; }
;     __device__ __forceinline__ void operator()(const f32x4 (&acc)[2][2][4][2], const Unit& u, int wr, int wc, int fr, int fq) const {
;         PG8_LAS const float* R = stage_rstd((const float*)(ws + WS_PS), lds, u.pm);
; #pragma unroll
;         for (int ai = 0; ai < 2; ++ai)
; #pragma unroll
;             for (int m = 0; m < 4; ++m) {
;                 const int row = u.pm * BM + ai * HALF + wr * 64 + m * 16 + fr;
;                 const float rs = R[ai * HALF + wr * 64 + m * 16 + fr];
;                 bf16_t* ACT = (bf16_t*)(ws + WS_ACT);
;                 f32x4 a[2];
; #pragma unroll
;                 for (int n = 0; n < 2; ++n) {
;                     const f32x4 g = acc[ai][0][m][n] * rs, uu = acc[ai][1][m][n] * rs;
; #pragma unroll
;                     for (int j = 0; j < 4; ++j) a[n][j] = g[j] * __builtin_amdgcn_rcpf(1.0f + __builtin_amdgcn_exp2f(-1.4426950408889634f * g[j])) * uu[j];
;                 }
;                 *(u32x4*)(ACT + (size_t)row * 2816 + u.pn * 128 + wc * 32 + 8 * fq) = pack8(a[0], a[1]);
.LBB0_38:
	s_lshl_b32 s3, s48, 8
	ds_read_b32 v146, v142
	v_mov_b32_e32 v145, 0xbfb8aa3b
	s_waitcnt lgkmcnt(0)
	v_pk_mul_f32 v[124:125], v[124:125], v[146:147] op_sel_hi:[1,0]
	v_pk_mul_f32 v[126:127], v[126:127], v[146:147] op_sel_hi:[1,0]
	v_pk_mul_f32 v[116:117], v[116:117], v[146:147] op_sel_hi:[1,0]
	v_pk_mul_f32 v[118:119], v[118:119], v[146:147] op_sel_hi:[1,0]
	v_pk_mul_f32 v[120:121], v[120:121], v[146:147] op_sel_hi:[1,0]
	v_pk_mul_f32 v[122:123], v[122:123], v[146:147] op_sel_hi:[1,0]
	v_pk_mul_f32 v[112:113], v[112:113], v[146:147] op_sel_hi:[1,0]
	v_pk_mul_f32 v[114:115], v[114:115], v[146:147] op_sel_hi:[1,0]
	v_pk_mul_f32 v[148:149], v[124:125], v[144:145] op_sel:[0,1] op_sel_hi:[1,1]
	v_exp_f32_e32 v148, v148
	v_exp_f32_e32 v149, v149
	v_add_f32_e32 v148, 1.0, v148
	v_add_f32_e32 v149, 1.0, v149
	v_rcp_f32_e32 v148, v148
	v_rcp_f32_e32 v149, v149
	s_nop 0
	v_pk_mul_f32 v[124:125], v[124:125], v[148:149]
	v_pk_mul_f32 v[120:121], v[120:121], v[124:125]
	v_pk_mul_f32 v[148:149], v[126:127], v[144:145] op_sel:[0,1] op_sel_hi:[1,1]
	v_exp_f32_e32 v148, v148
	v_exp_f32_e32 v149, v149
	v_add_f32_e32 v148, 1.0, v148
	v_add_f32_e32 v149, 1.0, v149
	v_rcp_f32_e32 v148, v148
	v_rcp_f32_e32 v149, v149
	s_nop 0
	v_pk_mul_f32 v[126:127], v[126:127], v[148:149]
	v_pk_mul_f32 v[122:123], v[122:123], v[126:127]
	v_pk_mul_f32 v[148:149], v[116:117], v[144:145] op_sel:[0,1] op_sel_hi:[1,1]
	v_exp_f32_e32 v148, v148
	v_exp_f32_e32 v149, v149
	v_add_f32_e32 v148, 1.0, v148
	v_add_f32_e32 v149, 1.0, v149
	v_rcp_f32_e32 v148, v148
	v_rcp_f32_e32 v149, v149
	s_nop 0
	v_pk_mul_f32 v[116:117], v[116:117], v[148:149]
	v_pk_mul_f32 v[112:113], v[112:113], v[116:117]
	v_pk_mul_f32 v[148:149], v[118:119], v[144:145] op_sel:[0,1] op_sel_hi:[1,1]
	v_exp_f32_e32 v148, v148
	v_exp_f32_e32 v149, v149
	v_add_f32_e32 v148, 1.0, v148
	v_add_f32_e32 v149, 1.0, v149
	v_rcp_f32_e32 v148, v148
	v_rcp_f32_e32 v149, v149
	s_nop 0
	v_pk_mul_f32 v[118:119], v[118:119], v[148:149]
	v_pk_mul_f32 v[114:115], v[114:115], v[118:119]
	v_cvt_pk_bf16_f32 v116, v112, v113
	v_cvt_pk_bf16_f32 v117, v114, v115
	v_cvt_pk_bf16_f32 v114, v120, v121
	v_cvt_pk_bf16_f32 v115, v122, v123
	s_lshl_b32 s0, s47, 7
	v_add_u32_e32 v144, s3, v140
	s_ashr_i32 s1, s0, 31
	s_movk_i32 s3, 0x1600
	s_lshl_b64 s[0:1], s[0:1], 1
	s_andn2_b64 vcc, exec, s[36:37]
	v_mov_b64_e32 v[112:113], s[16:17]
	s_mov_b32 s101, 0
	v_mad_i64_i32 v[118:119], s[4:5], v144, s3, v[112:113]
	v_lshl_add_u64 v[118:119], v[118:119], 0, s[0:1]
	v_lshl_add_u64 v[118:119], v[118:119], 0, s[34:35]
	v_lshl_add_u64 v[118:119], v[118:119], 0, v[184:185]
	global_store_dwordx4 v[118:119], v[114:117], off
	ds_read_b32 v114, v142 offset:64
	ds_read_b32 v120, v142 offset:128
	ds_read_b32 v122, v142 offset:192
	ds_read_b32 v124, v142 offset:512
	ds_read_b32 v126, v142 offset:576
	ds_read_b32 v112, v142 offset:640
	ds_read_b32 v116, v142 offset:704
	s_waitcnt lgkmcnt(6)
	v_pk_mul_f32 v[108:109], v[108:109], v[114:115] op_sel_hi:[1,0]
	v_pk_mul_f32 v[110:111], v[110:111], v[114:115] op_sel_hi:[1,0]
	v_pk_mul_f32 v[100:101], v[100:101], v[114:115] op_sel_hi:[1,0]
	v_pk_mul_f32 v[102:103], v[102:103], v[114:115] op_sel_hi:[1,0]
	v_pk_mul_f32 v[104:105], v[104:105], v[114:115] op_sel_hi:[1,0]
	v_pk_mul_f32 v[106:107], v[106:107], v[114:115] op_sel_hi:[1,0]
	v_pk_mul_f32 v[96:97], v[96:97], v[114:115] op_sel_hi:[1,0]
	v_pk_mul_f32 v[98:99], v[98:99], v[114:115] op_sel_hi:[1,0]
	v_pk_mul_f32 v[148:149], v[108:109], v[144:145] op_sel:[0,1] op_sel_hi:[1,1]
	v_exp_f32_e32 v148, v148
	v_exp_f32_e32 v149, v149
	v_add_f32_e32 v148, 1.0, v148
	v_add_f32_e32 v149, 1.0, v149
	v_rcp_f32_e32 v148, v148
	v_rcp_f32_e32 v149, v149
	s_nop 0
	v_pk_mul_f32 v[108:109], v[108:109], v[148:149]
	v_pk_mul_f32 v[104:105], v[104:105], v[108:109]
	v_pk_mul_f32 v[148:149], v[110:111], v[144:145] op_sel:[0,1] op_sel_hi:[1,1]
	v_exp_f32_e32 v148, v148
	v_exp_f32_e32 v149, v149
	v_add_f32_e32 v148, 1.0, v148
	v_add_f32_e32 v149, 1.0, v149
	v_rcp_f32_e32 v148, v148
	v_rcp_f32_e32 v149, v149
	s_nop 0
	v_pk_mul_f32 v[110:111], v[110:111], v[148:149]
	v_pk_mul_f32 v[106:107], v[106:107], v[110:111]
	v_pk_mul_f32 v[148:149], v[100:101], v[144:145] op_sel:[0,1] op_sel_hi:[1,1]
	v_exp_f32_e32 v148, v148
	v_exp_f32_e32 v149, v149
	v_add_f32_e32 v148, 1.0, v148
	v_add_f32_e32 v149, 1.0, v149
	v_rcp_f32_e32 v148, v148
	v_rcp_f32_e32 v149, v149
	s_nop 0
	v_pk_mul_f32 v[100:101], v[100:101], v[148:149]
	v_pk_mul_f32 v[96:97], v[96:97], v[100:101]
	v_pk_mul_f32 v[148:149], v[102:103], v[144:145] op_sel:[0,1] op_sel_hi:[1,1]
	v_exp_f32_e32 v148, v148
	v_exp_f32_e32 v149, v149
	v_add_f32_e32 v148, 1.0, v148
	v_add_f32_e32 v149, 1.0, v149
	v_rcp_f32_e32 v148, v148
	v_rcp_f32_e32 v149, v149
	s_nop 0
	v_pk_mul_f32 v[102:103], v[102:103], v[148:149]
	v_pk_mul_f32 v[98:99], v[98:99], v[102:103]
	v_cvt_pk_bf16_f32 v99, v98, v99
	v_cvt_pk_bf16_f32 v98, v96, v97
	v_cvt_pk_bf16_f32 v96, v104, v105
	v_cvt_pk_bf16_f32 v97, v106, v107
	s_mov_b32 s100, 0x16000
	v_lshl_add_u64 v[100:101], v[118:119], 0, s[100:101]
	global_store_dwordx4 v[100:101], v[96:99], off
	s_waitcnt lgkmcnt(0)
; __device__ __forceinline__ u32x4 pack8(const f32x4 a, const f32x4 b) { u32x4 w; w.x = cvt_pk_bf16(a[0], a[1]); w.y = cvt_pk_bf16(a[2], a[3]); w.z = cvt_pk_bf16(b[0], b[1]); w.w = cvt_pk_bf16(b[2], b[3]); return w; }
;     __device__ __forceinline__ void operator()(const f32x4 (&acc)[2][2][4][2], const Unit& u, int wr, int wc, int fr, int fq) const {
;     ...
;         for (int ai = 0; ai < 2; ++ai)
; #pragma unroll
;             for (int m = 0; m < 4; ++m) {
;                 const int row = u.pm * BM + ai * HALF + wr * 64 + m * 16 + fr;
;                 const float rs = R[ai * HALF + wr * 64 + m * 16 + fr];
;                 bf16_t* ACT = (bf16_t*)(ws + WS_ACT);
;                 f32x4 a[2];
; #pragma unroll
;                 for (int n = 0; n < 2; ++n) {
;                     const f32x4 g = acc[ai][0][m][n] * rs, uu = acc[ai][1][m][n] * rs;
; #pragma unroll
;                     for (int j = 0; j < 4; ++j) a[n][j] = g[j] * __builtin_amdgcn_rcpf(1.0f + __builtin_amdgcn_exp2f(-1.4426950408889634f * g[j])) * uu[j];
;                 }
;                 *(u32x4*)(ACT + (size_t)row * 2816 + u.pn * 128 + wc * 32 + 8 * fq) = pack8(a[0], a[1]);
;             }
	v_pk_mul_f32 v[92:93], v[92:93], v[120:121] op_sel_hi:[1,0]
	v_pk_mul_f32 v[94:95], v[94:95], v[120:121] op_sel_hi:[1,0]
	v_pk_mul_f32 v[84:85], v[84:85], v[120:121] op_sel_hi:[1,0]
	v_pk_mul_f32 v[86:87], v[86:87], v[120:121] op_sel_hi:[1,0]
	v_pk_mul_f32 v[88:89], v[88:89], v[120:121] op_sel_hi:[1,0]
	v_pk_mul_f32 v[90:91], v[90:91], v[120:121] op_sel_hi:[1,0]
	v_pk_mul_f32 v[80:81], v[80:81], v[120:121] op_sel_hi:[1,0]
	v_pk_mul_f32 v[82:83], v[82:83], v[120:121] op_sel_hi:[1,0]
	v_pk_mul_f32 v[148:149], v[92:93], v[144:145] op_sel:[0,1] op_sel_hi:[1,1]
	v_exp_f32_e32 v148, v148
	v_exp_f32_e32 v149, v149
	v_add_f32_e32 v148, 1.0, v148
	v_add_f32_e32 v149, 1.0, v149
	v_rcp_f32_e32 v148, v148
	v_rcp_f32_e32 v149, v149
	s_nop 0
	v_pk_mul_f32 v[92:93], v[92:93], v[148:149]
	v_pk_mul_f32 v[88:89], v[88:89], v[92:93]
	v_pk_mul_f32 v[148:149], v[94:95], v[144:145] op_sel:[0,1] op_sel_hi:[1,1]
	v_exp_f32_e32 v148, v148
	v_exp_f32_e32 v149, v149
	v_add_f32_e32 v148, 1.0, v148
	v_add_f32_e32 v149, 1.0, v149
	v_rcp_f32_e32 v148, v148
	v_rcp_f32_e32 v149, v149
	s_nop 0
	v_pk_mul_f32 v[94:95], v[94:95], v[148:149]
	v_pk_mul_f32 v[90:91], v[90:91], v[94:95]
	v_pk_mul_f32 v[148:149], v[84:85], v[144:145] op_sel:[0,1] op_sel_hi:[1,1]
	v_exp_f32_e32 v148, v148
	v_exp_f32_e32 v149, v149
	v_add_f32_e32 v148, 1.0, v148
	v_add_f32_e32 v149, 1.0, v149
	v_rcp_f32_e32 v148, v148
	v_rcp_f32_e32 v149, v149
	s_nop 0
	v_pk_mul_f32 v[84:85], v[84:85], v[148:149]
	v_pk_mul_f32 v[80:81], v[80:81], v[84:85]
	v_pk_mul_f32 v[148:149], v[86:87], v[144:145] op_sel:[0,1] op_sel_hi:[1,1]
	v_exp_f32_e32 v148, v148
	v_exp_f32_e32 v149, v149
	v_add_f32_e32 v148, 1.0, v148
	v_add_f32_e32 v149, 1.0, v149
	v_rcp_f32_e32 v148, v148
	v_rcp_f32_e32 v149, v149
	s_nop 0
	v_pk_mul_f32 v[86:87], v[86:87], v[148:149]
	v_pk_mul_f32 v[82:83], v[82:83], v[86:87]
	v_cvt_pk_bf16_f32 v83, v82, v83
	v_cvt_pk_bf16_f32 v82, v80, v81
	v_cvt_pk_bf16_f32 v80, v88, v89
	v_cvt_pk_bf16_f32 v81, v90, v91
	s_mov_b32 s100, 0x2c000
	v_lshl_add_u64 v[84:85], v[118:119], 0, s[100:101]
	global_store_dwordx4 v[84:85], v[80:83], off
	s_waitcnt lgkmcnt(0)
	v_pk_mul_f32 v[76:77], v[76:77], v[122:123] op_sel_hi:[1,0]
	v_pk_mul_f32 v[78:79], v[78:79], v[122:123] op_sel_hi:[1,0]
	v_pk_mul_f32 v[68:69], v[68:69], v[122:123] op_sel_hi:[1,0]
	v_pk_mul_f32 v[70:71], v[70:71], v[122:123] op_sel_hi:[1,0]
	v_pk_mul_f32 v[72:73], v[72:73], v[122:123] op_sel_hi:[1,0]
	v_pk_mul_f32 v[74:75], v[74:75], v[122:123] op_sel_hi:[1,0]
	v_pk_mul_f32 v[64:65], v[64:65], v[122:123] op_sel_hi:[1,0]
	v_pk_mul_f32 v[66:67], v[66:67], v[122:123] op_sel_hi:[1,0]
	v_pk_mul_f32 v[148:149], v[76:77], v[144:145] op_sel:[0,1] op_sel_hi:[1,1]
	v_exp_f32_e32 v148, v148
	v_exp_f32_e32 v149, v149
	v_add_f32_e32 v148, 1.0, v148
	v_add_f32_e32 v149, 1.0, v149
	v_rcp_f32_e32 v148, v148
	v_rcp_f32_e32 v149, v149
	s_nop 0
	v_pk_mul_f32 v[76:77], v[76:77], v[148:149]
	v_pk_mul_f32 v[72:73], v[72:73], v[76:77]
	v_pk_mul_f32 v[148:149], v[78:79], v[144:145] op_sel:[0,1] op_sel_hi:[1,1]
	v_exp_f32_e32 v148, v148
	v_exp_f32_e32 v149, v149
	v_add_f32_e32 v148, 1.0, v148
	v_add_f32_e32 v149, 1.0, v149
	v_rcp_f32_e32 v148, v148
	v_rcp_f32_e32 v149, v149
	s_nop 0
	v_pk_mul_f32 v[78:79], v[78:79], v[148:149]
	v_pk_mul_f32 v[74:75], v[74:75], v[78:79]
	v_pk_mul_f32 v[148:149], v[68:69], v[144:145] op_sel:[0,1] op_sel_hi:[1,1]
	v_exp_f32_e32 v148, v148
	v_exp_f32_e32 v149, v149
	v_add_f32_e32 v148, 1.0, v148
	v_add_f32_e32 v149, 1.0, v149
	v_rcp_f32_e32 v148, v148
	v_rcp_f32_e32 v149, v149
	s_nop 0
	v_pk_mul_f32 v[68:69], v[68:69], v[148:149]
	v_pk_mul_f32 v[64:65], v[64:65], v[68:69]
	v_pk_mul_f32 v[148:149], v[70:71], v[144:145] op_sel:[0,1] op_sel_hi:[1,1]
	v_exp_f32_e32 v148, v148
	v_exp_f32_e32 v149, v149
	v_add_f32_e32 v148, 1.0, v148
	v_add_f32_e32 v149, 1.0, v149
	v_rcp_f32_e32 v148, v148
	v_rcp_f32_e32 v149, v149
	s_nop 0
	v_pk_mul_f32 v[70:71], v[70:71], v[148:149]
	v_pk_mul_f32 v[66:67], v[66:67], v[70:71]
	v_cvt_pk_bf16_f32 v67, v66, v67
	v_cvt_pk_bf16_f32 v66, v64, v65
	v_cvt_pk_bf16_f32 v64, v72, v73
	v_cvt_pk_bf16_f32 v65, v74, v75
	s_mov_b32 s100, 0x42000
	v_lshl_add_u64 v[68:69], v[118:119], 0, s[100:101]
	global_store_dwordx4 v[68:69], v[64:67], off
	s_waitcnt lgkmcnt(0)
	v_pk_mul_f32 v[60:61], v[60:61], v[124:125] op_sel_hi:[1,0]
	v_pk_mul_f32 v[62:63], v[62:63], v[124:125] op_sel_hi:[1,0]
	v_pk_mul_f32 v[52:53], v[52:53], v[124:125] op_sel_hi:[1,0]
	v_pk_mul_f32 v[54:55], v[54:55], v[124:125] op_sel_hi:[1,0]
	v_pk_mul_f32 v[56:57], v[56:57], v[124:125] op_sel_hi:[1,0]
	v_pk_mul_f32 v[58:59], v[58:59], v[124:125] op_sel_hi:[1,0]
	v_pk_mul_f32 v[48:49], v[48:49], v[124:125] op_sel_hi:[1,0]
	v_pk_mul_f32 v[50:51], v[50:51], v[124:125] op_sel_hi:[1,0]
	v_pk_mul_f32 v[148:149], v[60:61], v[144:145] op_sel:[0,1] op_sel_hi:[1,1]
	v_exp_f32_e32 v148, v148
	v_exp_f32_e32 v149, v149
	v_add_f32_e32 v148, 1.0, v148
	v_add_f32_e32 v149, 1.0, v149
	v_rcp_f32_e32 v148, v148
	v_rcp_f32_e32 v149, v149
	s_nop 0
	v_pk_mul_f32 v[60:61], v[60:61], v[148:149]
	v_pk_mul_f32 v[56:57], v[56:57], v[60:61]
	v_pk_mul_f32 v[148:149], v[62:63], v[144:145] op_sel:[0,1] op_sel_hi:[1,1]
	v_exp_f32_e32 v148, v148
	v_exp_f32_e32 v149, v149
	v_add_f32_e32 v148, 1.0, v148
	v_add_f32_e32 v149, 1.0, v149
	v_rcp_f32_e32 v148, v148
	v_rcp_f32_e32 v149, v149
	s_nop 0
	v_pk_mul_f32 v[62:63], v[62:63], v[148:149]
	v_pk_mul_f32 v[58:59], v[58:59], v[62:63]
	v_pk_mul_f32 v[148:149], v[52:53], v[144:145] op_sel:[0,1] op_sel_hi:[1,1]
	v_exp_f32_e32 v148, v148
	v_exp_f32_e32 v149, v149
	v_add_f32_e32 v148, 1.0, v148
	v_add_f32_e32 v149, 1.0, v149
	v_rcp_f32_e32 v148, v148
	v_rcp_f32_e32 v149, v149
	s_nop 0
	v_pk_mul_f32 v[52:53], v[52:53], v[148:149]
	v_pk_mul_f32 v[48:49], v[48:49], v[52:53]
	v_pk_mul_f32 v[148:149], v[54:55], v[144:145] op_sel:[0,1] op_sel_hi:[1,1]
	v_exp_f32_e32 v148, v148
	v_exp_f32_e32 v149, v149
	v_add_f32_e32 v148, 1.0, v148
	v_add_f32_e32 v149, 1.0, v149
	v_rcp_f32_e32 v148, v148
	v_rcp_f32_e32 v149, v149
	s_nop 0
	v_pk_mul_f32 v[54:55], v[54:55], v[148:149]
	v_pk_mul_f32 v[50:51], v[50:51], v[54:55]
	v_cvt_pk_bf16_f32 v51, v50, v51
	v_cvt_pk_bf16_f32 v50, v48, v49
	v_cvt_pk_bf16_f32 v48, v56, v57
	v_cvt_pk_bf16_f32 v49, v58, v59
	s_mov_b32 s100, 0xb0000
	v_lshl_add_u64 v[52:53], v[118:119], 0, s[100:101]
	global_store_dwordx4 v[52:53], v[48:51], off
	s_waitcnt lgkmcnt(0)
; __device__ __forceinline__ u32x4 pack8(const f32x4 a, const f32x4 b) { u32x4 w; w.x = cvt_pk_bf16(a[0], a[1]); w.y = cvt_pk_bf16(a[2], a[3]); w.z = cvt_pk_bf16(b[0], b[1]); w.w = cvt_pk_bf16(b[2], b[3]); return w; }
;     __device__ __forceinline__ void operator()(const f32x4 (&acc)[2][2][4][2], const Unit& u, int wr, int wc, int fr, int fq) const {
;     ...
;         for (int ai = 0; ai < 2; ++ai)
; #pragma unroll
;             for (int m = 0; m < 4; ++m) {
;                 const int row = u.pm * BM + ai * HALF + wr * 64 + m * 16 + fr;
;                 const float rs = R[ai * HALF + wr * 64 + m * 16 + fr];
;                 bf16_t* ACT = (bf16_t*)(ws + WS_ACT);
;                 f32x4 a[2];
; #pragma unroll
;                 for (int n = 0; n < 2; ++n) {
;                     const f32x4 g = acc[ai][0][m][n] * rs, uu = acc[ai][1][m][n] * rs;
; #pragma unroll
;                     for (int j = 0; j < 4; ++j) a[n][j] = g[j] * __builtin_amdgcn_rcpf(1.0f + __builtin_amdgcn_exp2f(-1.4426950408889634f * g[j])) * uu[j];
;                 }
;                 *(u32x4*)(ACT + (size_t)row * 2816 + u.pn * 128 + wc * 32 + 8 * fq) = pack8(a[0], a[1]);
;             }
	v_pk_mul_f32 v[44:45], v[44:45], v[126:127] op_sel_hi:[1,0]
	v_pk_mul_f32 v[46:47], v[46:47], v[126:127] op_sel_hi:[1,0]
	v_pk_mul_f32 v[36:37], v[36:37], v[126:127] op_sel_hi:[1,0]
	v_pk_mul_f32 v[38:39], v[38:39], v[126:127] op_sel_hi:[1,0]
	v_pk_mul_f32 v[40:41], v[40:41], v[126:127] op_sel_hi:[1,0]
	v_pk_mul_f32 v[42:43], v[42:43], v[126:127] op_sel_hi:[1,0]
	v_pk_mul_f32 v[32:33], v[32:33], v[126:127] op_sel_hi:[1,0]
	v_pk_mul_f32 v[34:35], v[34:35], v[126:127] op_sel_hi:[1,0]
	v_pk_mul_f32 v[148:149], v[44:45], v[144:145] op_sel:[0,1] op_sel_hi:[1,1]
	v_exp_f32_e32 v148, v148
	v_exp_f32_e32 v149, v149
	v_add_f32_e32 v148, 1.0, v148
	v_add_f32_e32 v149, 1.0, v149
	v_rcp_f32_e32 v148, v148
	v_rcp_f32_e32 v149, v149
	s_nop 0
	v_pk_mul_f32 v[44:45], v[44:45], v[148:149]
	v_pk_mul_f32 v[40:41], v[40:41], v[44:45]
	v_pk_mul_f32 v[148:149], v[46:47], v[144:145] op_sel:[0,1] op_sel_hi:[1,1]
	v_exp_f32_e32 v148, v148
	v_exp_f32_e32 v149, v149
	v_add_f32_e32 v148, 1.0, v148
	v_add_f32_e32 v149, 1.0, v149
	v_rcp_f32_e32 v148, v148
	v_rcp_f32_e32 v149, v149
	s_nop 0
	v_pk_mul_f32 v[46:47], v[46:47], v[148:149]
	v_pk_mul_f32 v[42:43], v[42:43], v[46:47]
	v_pk_mul_f32 v[148:149], v[36:37], v[144:145] op_sel:[0,1] op_sel_hi:[1,1]
	v_exp_f32_e32 v148, v148
	v_exp_f32_e32 v149, v149
	v_add_f32_e32 v148, 1.0, v148
	v_add_f32_e32 v149, 1.0, v149
	v_rcp_f32_e32 v148, v148
	v_rcp_f32_e32 v149, v149
	s_nop 0
	v_pk_mul_f32 v[36:37], v[36:37], v[148:149]
	v_pk_mul_f32 v[32:33], v[32:33], v[36:37]
	v_pk_mul_f32 v[148:149], v[38:39], v[144:145] op_sel:[0,1] op_sel_hi:[1,1]
	v_exp_f32_e32 v148, v148
	v_exp_f32_e32 v149, v149
	v_add_f32_e32 v148, 1.0, v148
	v_add_f32_e32 v149, 1.0, v149
	v_rcp_f32_e32 v148, v148
	v_rcp_f32_e32 v149, v149
	s_nop 0
	v_pk_mul_f32 v[38:39], v[38:39], v[148:149]
	v_pk_mul_f32 v[34:35], v[34:35], v[38:39]
	v_cvt_pk_bf16_f32 v35, v34, v35
	v_cvt_pk_bf16_f32 v34, v32, v33
	v_cvt_pk_bf16_f32 v32, v40, v41
	v_cvt_pk_bf16_f32 v33, v42, v43
	s_mov_b32 s100, 0xc6000
	v_lshl_add_u64 v[36:37], v[118:119], 0, s[100:101]
	global_store_dwordx4 v[36:37], v[32:35], off
	s_waitcnt lgkmcnt(0)
	v_pk_mul_f32 v[28:29], v[28:29], v[112:113] op_sel_hi:[1,0]
	v_pk_mul_f32 v[30:31], v[30:31], v[112:113] op_sel_hi:[1,0]
	v_pk_mul_f32 v[20:21], v[20:21], v[112:113] op_sel_hi:[1,0]
	v_pk_mul_f32 v[22:23], v[22:23], v[112:113] op_sel_hi:[1,0]
	v_pk_mul_f32 v[24:25], v[24:25], v[112:113] op_sel_hi:[1,0]
	v_pk_mul_f32 v[26:27], v[26:27], v[112:113] op_sel_hi:[1,0]
	v_pk_mul_f32 v[16:17], v[16:17], v[112:113] op_sel_hi:[1,0]
	v_pk_mul_f32 v[18:19], v[18:19], v[112:113] op_sel_hi:[1,0]
	v_pk_mul_f32 v[148:149], v[28:29], v[144:145] op_sel:[0,1] op_sel_hi:[1,1]
	v_exp_f32_e32 v148, v148
	v_exp_f32_e32 v149, v149
	v_add_f32_e32 v148, 1.0, v148
	v_add_f32_e32 v149, 1.0, v149
	v_rcp_f32_e32 v148, v148
	v_rcp_f32_e32 v149, v149
	s_nop 0
	v_pk_mul_f32 v[28:29], v[28:29], v[148:149]
	v_pk_mul_f32 v[24:25], v[24:25], v[28:29]
	v_pk_mul_f32 v[148:149], v[30:31], v[144:145] op_sel:[0,1] op_sel_hi:[1,1]
	v_exp_f32_e32 v148, v148
	v_exp_f32_e32 v149, v149
	v_add_f32_e32 v148, 1.0, v148
	v_add_f32_e32 v149, 1.0, v149
	v_rcp_f32_e32 v148, v148
	v_rcp_f32_e32 v149, v149
	s_nop 0
	v_pk_mul_f32 v[30:31], v[30:31], v[148:149]
	v_pk_mul_f32 v[26:27], v[26:27], v[30:31]
	v_pk_mul_f32 v[148:149], v[20:21], v[144:145] op_sel:[0,1] op_sel_hi:[1,1]
	v_exp_f32_e32 v148, v148
	v_exp_f32_e32 v149, v149
	v_add_f32_e32 v148, 1.0, v148
	v_add_f32_e32 v149, 1.0, v149
	v_rcp_f32_e32 v148, v148
	v_rcp_f32_e32 v149, v149
	s_nop 0
	v_pk_mul_f32 v[20:21], v[20:21], v[148:149]
	v_pk_mul_f32 v[16:17], v[16:17], v[20:21]
	v_pk_mul_f32 v[148:149], v[22:23], v[144:145] op_sel:[0,1] op_sel_hi:[1,1]
	v_exp_f32_e32 v148, v148
	v_exp_f32_e32 v149, v149
	v_add_f32_e32 v148, 1.0, v148
	v_add_f32_e32 v149, 1.0, v149
	v_rcp_f32_e32 v148, v148
	v_rcp_f32_e32 v149, v149
	s_nop 0
	v_pk_mul_f32 v[22:23], v[22:23], v[148:149]
	v_pk_mul_f32 v[18:19], v[18:19], v[22:23]
	v_cvt_pk_bf16_f32 v19, v18, v19
	v_cvt_pk_bf16_f32 v18, v16, v17
	v_cvt_pk_bf16_f32 v16, v24, v25
	v_cvt_pk_bf16_f32 v17, v26, v27
	s_mov_b32 s100, 0xdc000
	v_lshl_add_u64 v[20:21], v[118:119], 0, s[100:101]
	global_store_dwordx4 v[20:21], v[16:19], off
	s_waitcnt lgkmcnt(0)
	v_pk_mul_f32 v[12:13], v[12:13], v[116:117] op_sel_hi:[1,0]
	v_pk_mul_f32 v[14:15], v[14:15], v[116:117] op_sel_hi:[1,0]
	v_pk_mul_f32 v[4:5], v[4:5], v[116:117] op_sel_hi:[1,0]
	v_pk_mul_f32 v[6:7], v[6:7], v[116:117] op_sel_hi:[1,0]
	v_pk_mul_f32 v[8:9], v[8:9], v[116:117] op_sel_hi:[1,0]
	v_pk_mul_f32 v[10:11], v[10:11], v[116:117] op_sel_hi:[1,0]
	v_pk_mul_f32 v[0:1], v[0:1], v[116:117] op_sel_hi:[1,0]
	v_pk_mul_f32 v[2:3], v[2:3], v[116:117] op_sel_hi:[1,0]
	v_pk_mul_f32 v[148:149], v[12:13], v[144:145] op_sel:[0,1] op_sel_hi:[1,1]
	v_exp_f32_e32 v148, v148
	v_exp_f32_e32 v149, v149
	v_add_f32_e32 v148, 1.0, v148
	v_add_f32_e32 v149, 1.0, v149
	v_rcp_f32_e32 v148, v148
	v_rcp_f32_e32 v149, v149
	s_nop 0
	v_pk_mul_f32 v[12:13], v[12:13], v[148:149]
	v_pk_mul_f32 v[8:9], v[8:9], v[12:13]
	v_pk_mul_f32 v[148:149], v[14:15], v[144:145] op_sel:[0,1] op_sel_hi:[1,1]
	v_exp_f32_e32 v148, v148
	v_exp_f32_e32 v149, v149
	v_add_f32_e32 v148, 1.0, v148
	v_add_f32_e32 v149, 1.0, v149
	v_rcp_f32_e32 v148, v148
	v_rcp_f32_e32 v149, v149
	s_nop 0
	v_pk_mul_f32 v[14:15], v[14:15], v[148:149]
	v_pk_mul_f32 v[10:11], v[10:11], v[14:15]
	v_pk_mul_f32 v[148:149], v[4:5], v[144:145] op_sel:[0,1] op_sel_hi:[1,1]
	v_exp_f32_e32 v148, v148
	v_exp_f32_e32 v149, v149
	v_add_f32_e32 v148, 1.0, v148
	v_add_f32_e32 v149, 1.0, v149
	v_rcp_f32_e32 v148, v148
	v_rcp_f32_e32 v149, v149
	s_nop 0
	v_pk_mul_f32 v[4:5], v[4:5], v[148:149]
	v_pk_mul_f32 v[0:1], v[0:1], v[4:5]
	v_pk_mul_f32 v[148:149], v[6:7], v[144:145] op_sel:[0,1] op_sel_hi:[1,1]
	v_exp_f32_e32 v148, v148
	v_exp_f32_e32 v149, v149
	v_add_f32_e32 v148, 1.0, v148
	v_add_f32_e32 v149, 1.0, v149
	v_rcp_f32_e32 v148, v148
	v_rcp_f32_e32 v149, v149
	s_nop 0
	v_pk_mul_f32 v[6:7], v[6:7], v[148:149]
	v_pk_mul_f32 v[2:3], v[2:3], v[6:7]
	v_cvt_pk_bf16_f32 v3, v2, v3
	v_cvt_pk_bf16_f32 v2, v0, v1
	v_cvt_pk_bf16_f32 v0, v8, v9
	v_cvt_pk_bf16_f32 v1, v10, v11
	s_mov_b32 s100, 0xf2000
	v_lshl_add_u64 v[4:5], v[118:119], 0, s[100:101]
	s_mov_b64 s[0:1], -1
	global_store_dwordx4 v[4:5], v[0:3], off
	s_cbranch_vccnz .LBB0_31
	s_andn2_b64 vcc, exec, s[8:9]
	s_cbranch_vccnz .LBB0_30
	s_barrier
	s_branch .LBB0_30
